# S5 pass 2: H-tile staging loads left in flight while the forward direction's parameter/state/carry-in loads are issued; LDS write + barrier moved to just before the scan
# baseline (speedup 1.0000x reference)
.LBB0_194:
	s_ashr_i32 s9, s8, 3
	s_and_b32 s4, s8, 7
	s_waitcnt vmcnt(0) lgkmcnt(0)
	s_barrier
	s_and_saveexec_b64 s[14:15], s[12:13]
	s_movk_i32 s5, 0x110
	s_movk_i32 s33, 0xdff
	s_cbranch_execz .LBB0_197
	s_lshl_b32 s38, s4, 8
	s_mov_b32 s39, 0
	s_lshl_b32 s3, s9, 8
	v_lshl_add_u64 v[0:1], v[172:173], 0, s[38:39]
	v_ashrrev_i32_e32 v3, 4, v210
	v_add_u32_e32 v4, s3, v3
	v_ashrrev_i32_e32 v5, 31, v4
	v_lshlrev_b64 v[4:5], 11, v[4:5]
	v_lshl_add_u64 v[4:5], v[0:1], 0, v[4:5]
	s_mov_b64 s[34:35], 0x10000
	v_mad_u64_u32 v[140:141], vcc, v3, s5, v[174:175]
	global_load_dwordx4 v[72:75], v[4:5], off
	v_lshl_add_u64 v[4:5], v[4:5], 0, s[34:35]
	global_load_dwordx4 v[76:79], v[4:5], off
	v_lshl_add_u64 v[4:5], v[4:5], 0, s[34:35]
	global_load_dwordx4 v[80:83], v[4:5], off
	v_lshl_add_u64 v[4:5], v[4:5], 0, s[34:35]
	global_load_dwordx4 v[84:87], v[4:5], off
	v_lshl_add_u64 v[4:5], v[4:5], 0, s[34:35]
	global_load_dwordx4 v[88:91], v[4:5], off
	v_lshl_add_u64 v[4:5], v[4:5], 0, s[34:35]
	global_load_dwordx4 v[92:95], v[4:5], off
	v_lshl_add_u64 v[4:5], v[4:5], 0, s[34:35]
	global_load_dwordx4 v[96:99], v[4:5], off
	v_lshl_add_u64 v[4:5], v[4:5], 0, s[34:35]
	global_load_dwordx4 v[136:139], v[4:5], off
.LBB0_197:
	s_or_b64 exec, exec, s[14:15]
	s_lshl_b32 s3, s4, 3
	v_readlane_b32 s5, v238, 0
	s_add_i32 s14, s3, s5
	v_readlane_b32 s3, v238, 2
	s_add_i32 s34, s14, s3
	s_ashr_i32 s35, s34, 31
	s_lshl_b64 s[42:43], s[34:35], 12
	s_lshl_b64 s[34:35], s[34:35], 9
	s_add_u32 s38, s65, s34
	v_lshl_add_u64 v[0:1], v[178:179], 0, s[42:43]
	s_addc_u32 s39, s72, s35
	v_lshlrev_b32_e32 v164, 2, v170
	flat_load_dwordx4 v[124:127], v[0:1]
	flat_load_dwordx4 v[120:123], v[0:1] offset:1024
	flat_load_dwordx4 v[128:131], v[0:1] offset:2048
	flat_load_dwordx4 v[116:119], v[0:1] offset:3072
	v_lshl_add_u64 v[0:1], s[38:39], 0, v[164:165]
	v_mov_b32_e32 v185, v165
	flat_load_dwordx2 v[132:133], v[0:1]
	v_lshl_add_u64 v[0:1], s[38:39], 0, v[184:185]
	v_mov_b32_e32 v187, v165
	flat_load_dword v134, v[0:1]
	v_lshl_add_u64 v[0:1], s[38:39], 0, v[186:187]
	s_lshl_b32 s38, s9, 1
	s_add_u32 s34, s6, s34
	flat_load_dword v135, v[0:1]
	v_lshl_add_u64 v[0:1], v[180:181], 0, s[42:43]
	s_addc_u32 s35, s7, s35
	flat_load_dwordx4 v[112:115], v[0:1]
	flat_load_dwordx4 v[108:111], v[0:1] offset:64
	flat_load_dwordx4 v[104:107], v[0:1] offset:128
	flat_load_dwordx4 v[100:103], v[0:1] offset:192
	v_lshl_add_u64 v[0:1], s[34:35], 0, v[164:165]
	flat_load_dwordx2 v[2:3], v[0:1]
	v_lshl_add_u64 v[0:1], s[34:35], 0, v[184:185]
	v_lshl_add_u64 v[4:5], s[34:35], 0, v[186:187]
	flat_load_dword v1, v[0:1]
	s_cmp_lt_i32 s9, 16
	flat_load_dword v0, v[4:5]
	s_cselect_b64 s[34:35], -1, 0
	s_cmp_gt_i32 s9, 15
	s_cselect_b64 s[46:47], -1, 0
	v_mov_b32_e32 v4, 0
	s_mov_b32 s61, s72
	s_and_b64 vcc, exec, s[46:47]
	s_mov_b32 s42, s38
	v_mov_b32_e32 v5, 0
	v_mov_b32_e32 v6, 0
	v_mov_b32_e32 v7, v4
	s_cbranch_vccz .LBB0_199
	s_add_i32 s3, s9, -16
	s_lshr_b32 s3, s3, 3
	s_lshl_b32 s5, s3, 4
	s_lshl_b32 s3, s3, 2
	s_add_i32 s50, s3, s79
	s_ashr_i32 s51, s50, 31
	s_lshl_b32 s3, s14, 6
	s_add_i32 s42, s5, 32
	s_lshl_b64 s[50:51], s[50:51], 12
	s_ashr_i32 s5, s3, 31
	s_add_u32 s3, s50, s3
	s_addc_u32 s5, s51, s5
	v_mov_b32_e32 v5, s5
	v_or_b32_e32 v4, s3, v168
	v_readlane_b32 s76, v239, 31
	v_lshlrev_b64 v[4:5], 2, v[4:5]
	v_readlane_b32 s80, v239, 35
	v_readlane_b32 s81, v239, 36
	v_readlane_b32 s82, v239, 37
	v_readlane_b32 s83, v239, 38
	v_lshl_add_u64 v[8:9], s[80:81], 0, v[4:5]
	v_readlane_b32 s78, v239, 33
	v_lshl_add_u64 v[10:11], s[82:83], 0, v[4:5]
	global_load_dword v7, v[8:9], off
	global_load_dword v5, v[8:9], off offset:128
	global_load_dword v6, v[10:11], off
	global_load_dword v4, v[10:11], off offset:128
	v_readlane_b32 s79, v239, 34
	v_readlane_b32 s79, v238, 11
	v_readlane_b32 s78, v238, 9
	v_readlane_b32 s77, v239, 32
	v_readlane_b32 s84, v239, 39
	v_readlane_b32 s85, v239, 40
	v_readlane_b32 s86, v239, 41
	v_readlane_b32 s87, v239, 42
	v_readlane_b32 s88, v239, 43
	v_readlane_b32 s89, v239, 44
	v_readlane_b32 s90, v239, 45
	v_readlane_b32 s91, v239, 46

.LBB0_205:
	s_waitcnt vmcnt(0)
	s_and_saveexec_b64 s[52:53], s[12:13]
	ds_write_b128 v140, v[72:75]
	ds_write_b128 v140, v[76:79] offset:8704
	ds_write_b128 v140, v[80:83] offset:17408
	ds_write_b128 v140, v[84:87] offset:26112
	ds_write_b128 v140, v[88:91] offset:34816
	ds_write_b128 v140, v[92:95] offset:43520
	ds_write_b128 v140, v[96:99] offset:52224
	ds_write_b128 v140, v[136:139] offset:60928
	s_or_b64 exec, exec, s[52:53]
	s_waitcnt lgkmcnt(0)
	s_barrier
	ds_read_b128 v[32:35], v212
	v_readlane_b32 s42, v239, 47
	s_add_i32 s3, s38, s42
	v_readlane_b32 s43, v239, 48
	s_lshl_b32 s42, s3, 1
	s_lshl_b32 s5, s14, 6
	s_ashr_i32 s43, s42, 31
	s_ashr_i32 s15, s5, 31
	s_lshl_b64 s[52:53], s[42:43], 12
	s_waitcnt vmcnt(0) lgkmcnt(0)
	v_mfma_f32_32x32x16_bf16 v[0:15], v[32:35], v[124:127], 0
	s_add_u32 s3, s52, s5
	s_addc_u32 s33, s53, s15
	v_readlane_b32 s52, v239, 60
	v_or_b32_e32 v38, s3, v166
	v_readlane_b32 s53, v239, 61
	v_mov_b32_e32 v39, s33
	s_and_b64 s[70:71], s[34:35], s[52:53]
	v_mfma_f32_32x32x16_bf16 v[16:31], v[32:35], v[128:131], 0
	s_nop 3
	v_fma_f32 v0, -v133, v37, v0
	v_fmac_f32_e32 v0, v132, v36
	v_lshlrev_b64 v[64:65], 2, v[38:39]
	s_nop 4
	v_fma_f32 v16, v133, v36, v16
	v_fmac_f32_e32 v16, v132, v37
	s_and_saveexec_b64 s[72:73], s[70:71]
	s_cbranch_execz .LBB0_207
	v_lshl_add_u64 v[36:37], s[10:11], 0, v[64:65]
	v_lshl_add_u64 v[38:39], s[18:19], 0, v[64:65]
	global_store_dword v[36:37], v0, off
	global_store_dword v[38:39], v16, off
